# hin x2|v epilogue regenerated column-major: one address per column, fragments m/m+1 exchanged with v_permlane16_swap, 16-byte stores
# speedup vs baseline: 1.0540x; 1.0045x over previous
; template <bool SWAP, class Epi, bool THIN = false> ...
;     ...
;     for (int st = 0; st < ns; ++st) {
;       asm volatile("s_waitcnt vmcnt(0)" ::: "memory");
;       __builtin_amdgcn_s_barrier();
;       asm volatile("" ::: "memory");
;       if (st + 1 < ns) {
;         char* nb = smem + ((st + 1) & 1) * 65536;
;         const int ko = (st + 1) * 64;
; #pragma unroll
;         for (int i = 0; i < 4; ++i) { GLDS16(A + (size_t)(ap[i] + ko), nb + tid * 16 + i * 8192); GLDS16(Bt + (size_t)(bp[i] + ko), nb + 32768 + tid * 16 + i * 8192); }
;       }
;       const char* sa = smem + (st & 1) * 65536 + (wr * 64 + fr) * 128;
;       const char* sb = smem + (st & 1) * 65536 + 32768 + (wc * 128 + fr) * 128;
;       if constexpr (THIN) {
;         if (wc == 0) {
; #pragma unroll
;           for (int ks = 0; ks < 2; ++ks) {
;             bf16x8 af[4], bf[2];
; #pragma unroll
;             for (int m = 0; m < 4; ++m) af[m] = *(const bf16x8*)(sa + m * 2048 + (((ks * 4 + fq) ^ swz) << 4));
; #pragma unroll
;             for (int n = 0; n < 2; ++n) bf[n] = *(const bf16x8*)(sb + n * 2048 + (((ks * 4 + fq) ^ swz) << 4));
; #pragma unroll
;             for (int m = 0; m < 4; ++m)
; #pragma unroll
;               for (int n = 0; n < 2; ++n)
;                 acc[m][n] = SWAP ? __builtin_amdgcn_mfma_f32_16x16x32_bf16(bf[n], af[m], acc[m][n], 0, 0, 0)
;                                  : __builtin_amdgcn_mfma_f32_16x16x32_bf16(af[m], bf[n], acc[m][n], 0, 0, 0);
;           }
;         }
;       } else {
;       bf16x8 afA[4], afB[4], bfb[2][2];
; #pragma unroll
;       for (int m = 0; m < 4; ++m) afA[m] = *(const bf16x8*)(sa + m * 2048 + ((fq ^ swz) << 4));
; #pragma unroll
;       for (int n = 0; n < 2; ++n) bfb[0][n] = *(const bf16x8*)(sb + n * 2048 + ((fq ^ swz) << 4));
; #pragma unroll
;       for (int gq = 0; gq < 8; ++gq) {
;         const int ks = gq >> 2, nh = gq & 3;
;         if (gq < 7) {
;           const int ks2 = (gq + 1) >> 2, nh2 = (gq + 1) & 3;
; #pragma unroll
;           for (int n = 0; n < 2; ++n) bfb[(gq + 1) & 1][n] = *(const bf16x8*)(sb + (nh2 * 2 + n) * 2048 + (((ks2 * 4 + fq) ^ swz) << 4));
;         }
;         if (gq == 3) {
; #pragma unroll
;           for (int m = 0; m < 4; ++m) afB[m] = *(const bf16x8*)(sa + m * 2048 + (((4 + fq) ^ swz) << 4));
;         }
;         __builtin_amdgcn_sched_barrier(0);
; #pragma unroll
.LBB0_2714:
	s_add_i32 s8, s7, 0x10000
	s_and_b32 s9, s8, 0x10000
	v_add_u32_e32 v167, s9, v138
	s_nop 0
	v_readfirstlane_b32 s9, v167
	s_waitcnt vmcnt(0)
	s_barrier
	s_and_b32 s7, s7, 0x10000
	v_add_u32_e32 v130, s7, v139
	v_add_u32_e32 v167, v130, v141
	ds_read_b128 v[168:171], v167
	ds_read_b128 v[172:175], v167 offset:2048
	ds_read_b128 v[176:179], v167 offset:4096
	ds_read_b128 v[180:183], v167 offset:6144
	v_or_b32_e32 v167, s7, v140
	v_add_u32_e32 v204, v167, v141
	ds_read_b128 v[184:187], v204 offset:32768
	ds_read_b128 v[188:191], v204 offset:34816
	ds_read_b128 v[192:195], v204 offset:36864
	ds_read_b128 v[196:199], v204 offset:38912
	v_add_u32_e32 v130, v130, v142
	s_waitcnt lgkmcnt(3)
	v_mfma_f32_16x16x32_bf16 v[126:129], v[168:171], v[184:187], v[126:129]
	s_mov_b32 m0, s9
	v_mfma_f32_16x16x32_bf16 v[110:113], v[172:175], v[184:187], v[110:113]
	global_load_lds_dwordx4 v166, s[18:19]
	v_add_u32_e32 v166, 0x80, v166
	v_mfma_f32_16x16x32_bf16 v[82:85], v[176:179], v[184:187], v[82:85]
	v_mfma_f32_16x16x32_bf16 v[50:53], v[180:183], v[184:187], v[50:53]
	ds_read_b128 v[184:187], v204 offset:40960
	ds_read_b128 v[200:203], v204 offset:43008
	s_waitcnt lgkmcnt(4)
	v_mfma_f32_16x16x32_bf16 v[122:125], v[168:171], v[188:191], v[122:125]
	s_add_u32 m0, s9, 0x8000
	v_mfma_f32_16x16x32_bf16 v[106:109], v[172:175], v[188:191], v[106:109]
	global_load_lds_dwordx4 v165, s[24:25]
	v_add_u32_e32 v165, 0x80, v165
	v_mfma_f32_16x16x32_bf16 v[78:81], v[176:179], v[188:191], v[78:81]
	v_mfma_f32_16x16x32_bf16 v[42:45], v[180:183], v[188:191], v[42:45]
	s_waitcnt lgkmcnt(3)
	v_mfma_f32_16x16x32_bf16 v[118:121], v[168:171], v[192:195], v[118:121]
	s_add_u32 m0, s9, 0x2000
	v_mfma_f32_16x16x32_bf16 v[94:97], v[172:175], v[192:195], v[94:97]
	global_load_lds_dwordx4 v164, s[18:19]
	v_add_u32_e32 v164, 0x80, v164
	v_mfma_f32_16x16x32_bf16 v[58:61], v[176:179], v[192:195], v[58:61]
	v_mfma_f32_16x16x32_bf16 v[26:29], v[180:183], v[192:195], v[26:29]
	ds_read_b128 v[188:191], v204 offset:45056
	ds_read_b128 v[192:195], v204 offset:47104
	s_waitcnt lgkmcnt(4)
	v_mfma_f32_16x16x32_bf16 v[114:117], v[168:171], v[196:199], v[114:117]
	s_add_u32 m0, s9, 0xa000
	v_mfma_f32_16x16x32_bf16 v[86:89], v[172:175], v[196:199], v[86:89]
	global_load_lds_dwordx4 v163, s[24:25]
	v_add_u32_e32 v163, 0x80, v163
	v_mfma_f32_16x16x32_bf16 v[54:57], v[176:179], v[196:199], v[54:57]
	v_mfma_f32_16x16x32_bf16 v[22:25], v[180:183], v[196:199], v[22:25]
	v_add_u32_e32 v167, v167, v142
	s_waitcnt lgkmcnt(3)
	v_mfma_f32_16x16x32_bf16 v[102:105], v[168:171], v[184:187], v[102:105]
	ds_read_b128 v[196:199], v167 offset:32768
	ds_read_b128 v[204:207], v167 offset:34816
	s_add_u32 m0, s9, 0x4000
	v_mfma_f32_16x16x32_bf16 v[74:77], v[172:175], v[184:187], v[74:77]
	global_load_lds_dwordx4 v135, s[18:19]
	v_add_u32_e32 v135, 0x80, v135
	v_mfma_f32_16x16x32_bf16 v[46:49], v[176:179], v[184:187], v[46:49]
	v_mfma_f32_16x16x32_bf16 v[10:13], v[180:183], v[184:187], v[10:13]
	ds_read_b128 v[184:187], v130
	ds_read_b128 v[208:211], v130 offset:2048
	ds_read_b128 v[212:215], v130 offset:4096
	ds_read_b128 v[216:219], v130 offset:6144
	s_waitcnt lgkmcnt(8)
	v_mfma_f32_16x16x32_bf16 v[98:101], v[168:171], v[200:203], v[98:101]
	s_add_u32 m0, s9, 0xc000
	v_mfma_f32_16x16x32_bf16 v[66:69], v[172:175], v[200:203], v[66:69]
	global_load_lds_dwordx4 v134, s[24:25]
	v_add_u32_e32 v134, 0x80, v134
	v_mfma_f32_16x16x32_bf16 v[30:33], v[176:179], v[200:203], v[30:33]
	v_mfma_f32_16x16x32_bf16 v[6:9], v[180:183], v[200:203], v[6:9]
	s_waitcnt lgkmcnt(7)
	v_mfma_f32_16x16x32_bf16 v[70:73], v[168:171], v[188:191], v[70:73]
	s_add_u32 m0, s9, 0x6000
	s_waitcnt lgkmcnt(6)
	v_mfma_f32_16x16x32_bf16 v[62:65], v[168:171], v[192:195], v[62:65]
	global_load_lds_dwordx4 v133, s[18:19]
	v_add_u32_e32 v133, 0x80, v133
	v_mfma_f32_16x16x32_bf16 v[38:41], v[172:175], v[188:191], v[38:41]
	v_mfma_f32_16x16x32_bf16 v[34:37], v[172:175], v[192:195], v[34:37]
	ds_read_b128 v[168:171], v167 offset:36864
	ds_read_b128 v[172:175], v167 offset:38912
	v_mfma_f32_16x16x32_bf16 v[18:21], v[176:179], v[188:191], v[18:21]
	s_add_u32 m0, s9, 0xe000
	v_mfma_f32_16x16x32_bf16 v[14:17], v[176:179], v[192:195], v[14:17]
	global_load_lds_dwordx4 v132, s[24:25]
	v_add_u32_e32 v132, 0x80, v132
	v_mfma_f32_16x16x32_bf16 v[2:5], v[180:183], v[188:191], v[2:5]
	v_mfma_f32_16x16x32_bf16 v[90:93], v[180:183], v[192:195], v[90:93]
	ds_read_b128 v[176:179], v167 offset:40960
	ds_read_b128 v[180:183], v167 offset:43008
	s_waitcnt lgkmcnt(7)
	v_mfma_f32_16x16x32_bf16 v[126:129], v[184:187], v[196:199], v[126:129]
	v_mfma_f32_16x16x32_bf16 v[122:125], v[184:187], v[204:207], v[122:125]
	s_waitcnt lgkmcnt(6)
	v_mfma_f32_16x16x32_bf16 v[110:113], v[208:211], v[196:199], v[110:113]
	v_mfma_f32_16x16x32_bf16 v[106:109], v[208:211], v[204:207], v[106:109]
	s_waitcnt lgkmcnt(5)
	v_mfma_f32_16x16x32_bf16 v[82:85], v[212:215], v[196:199], v[82:85]
	v_mfma_f32_16x16x32_bf16 v[78:81], v[212:215], v[204:207], v[78:81]
	s_waitcnt lgkmcnt(4)
	v_mfma_f32_16x16x32_bf16 v[50:53], v[216:219], v[196:199], v[50:53]
	v_mfma_f32_16x16x32_bf16 v[42:45], v[216:219], v[204:207], v[42:45]
	s_waitcnt lgkmcnt(3)
	v_mfma_f32_16x16x32_bf16 v[118:121], v[184:187], v[168:171], v[118:121]
	v_mfma_f32_16x16x32_bf16 v[94:97], v[208:211], v[168:171], v[94:97]
	v_mfma_f32_16x16x32_bf16 v[58:61], v[212:215], v[168:171], v[58:61]
	v_mfma_f32_16x16x32_bf16 v[26:29], v[216:219], v[168:171], v[26:29]
	ds_read_b128 v[168:171], v167 offset:45056
	ds_read_b128 v[188:191], v167 offset:47104
	s_waitcnt lgkmcnt(4)
; template <bool SWAP, class Epi, bool THIN = false> ...
;     ...
;     for (int st = 0; st < ns; ++st) {
;       asm volatile("s_waitcnt vmcnt(0)" ::: "memory");
;       __builtin_amdgcn_s_barrier();
;       asm volatile("" ::: "memory");
;       if (st + 1 < ns) {
;         char* nb = smem + ((st + 1) & 1) * 65536;
;         const int ko = (st + 1) * 64;
; #pragma unroll
;         for (int i = 0; i < 4; ++i) { GLDS16(A + (size_t)(ap[i] + ko), nb + tid * 16 + i * 8192); GLDS16(Bt + (size_t)(bp[i] + ko), nb + 32768 + tid * 16 + i * 8192); }
;       }
;       const char* sa = smem + (st & 1) * 65536 + (wr * 64 + fr) * 128;
;       const char* sb = smem + (st & 1) * 65536 + 32768 + (wc * 128 + fr) * 128;
;       if constexpr (THIN) {
;         if (wc == 0) {
; #pragma unroll
;           for (int ks = 0; ks < 2; ++ks) {
;             bf16x8 af[4], bf[2];
; #pragma unroll
;             for (int m = 0; m < 4; ++m) af[m] = *(const bf16x8*)(sa + m * 2048 + (((ks * 4 + fq) ^ swz) << 4));
; #pragma unroll
;             for (int n = 0; n < 2; ++n) bf[n] = *(const bf16x8*)(sb + n * 2048 + (((ks * 4 + fq) ^ swz) << 4));
; #pragma unroll
;             for (int m = 0; m < 4; ++m)
; #pragma unroll
;               for (int n = 0; n < 2; ++n)
;                 acc[m][n] = SWAP ? __builtin_amdgcn_mfma_f32_16x16x32_bf16(bf[n], af[m], acc[m][n], 0, 0, 0)
;                                  : __builtin_amdgcn_mfma_f32_16x16x32_bf16(af[m], bf[n], acc[m][n], 0, 0, 0);
;           }
;         }
;       } else {
;       bf16x8 afA[4], afB[4], bfb[2][2];
; #pragma unroll
;       for (int m = 0; m < 4; ++m) afA[m] = *(const bf16x8*)(sa + m * 2048 + ((fq ^ swz) << 4));
; #pragma unroll
;       for (int n = 0; n < 2; ++n) bfb[0][n] = *(const bf16x8*)(sb + n * 2048 + ((fq ^ swz) << 4));
; #pragma unroll
;       for (int gq = 0; gq < 8; ++gq) {
;         const int ks = gq >> 2, nh = gq & 3;
;         if (gq < 7) {
;           const int ks2 = (gq + 1) >> 2, nh2 = (gq + 1) & 3;
; #pragma unroll
;           for (int n = 0; n < 2; ++n) bfb[(gq + 1) & 1][n] = *(const bf16x8*)(sb + (nh2 * 2 + n) * 2048 + (((ks2 * 4 + fq) ^ swz) << 4));
;         }
;         if (gq == 3) {
; #pragma unroll
;           for (int m = 0; m < 4; ++m) afB[m] = *(const bf16x8*)(sa + m * 2048 + (((4 + fq) ^ swz) << 4));
;         }
;         __builtin_amdgcn_sched_barrier(0);
; #pragma unroll
	v_mfma_f32_16x16x32_bf16 v[114:117], v[184:187], v[172:175], v[114:117]
	v_mfma_f32_16x16x32_bf16 v[86:89], v[208:211], v[172:175], v[86:89]
	v_mfma_f32_16x16x32_bf16 v[54:57], v[212:215], v[172:175], v[54:57]
	v_mfma_f32_16x16x32_bf16 v[22:25], v[216:219], v[172:175], v[22:25]
	s_waitcnt lgkmcnt(3)
	v_mfma_f32_16x16x32_bf16 v[102:105], v[184:187], v[176:179], v[102:105]
	s_waitcnt lgkmcnt(2)
	v_mfma_f32_16x16x32_bf16 v[98:101], v[184:187], v[180:183], v[98:101]
	v_mfma_f32_16x16x32_bf16 v[74:77], v[208:211], v[176:179], v[74:77]
	v_mfma_f32_16x16x32_bf16 v[66:69], v[208:211], v[180:183], v[66:69]
	v_mfma_f32_16x16x32_bf16 v[46:49], v[212:215], v[176:179], v[46:49]
	v_mfma_f32_16x16x32_bf16 v[30:33], v[212:215], v[180:183], v[30:33]
	v_mfma_f32_16x16x32_bf16 v[10:13], v[216:219], v[176:179], v[10:13]
	v_mfma_f32_16x16x32_bf16 v[6:9], v[216:219], v[180:183], v[6:9]
	s_waitcnt lgkmcnt(1)
	v_mfma_f32_16x16x32_bf16 v[70:73], v[184:187], v[168:171], v[70:73]
	s_add_i32 s6, s6, 64
	s_cmpk_eq_i32 s6, 0x3c0
	s_mov_b32 s7, s8
	s_waitcnt lgkmcnt(0)
	v_mfma_f32_16x16x32_bf16 v[62:65], v[184:187], v[188:191], v[62:65]
	v_mfma_f32_16x16x32_bf16 v[38:41], v[208:211], v[168:171], v[38:41]
	v_mfma_f32_16x16x32_bf16 v[34:37], v[208:211], v[188:191], v[34:37]
	v_mfma_f32_16x16x32_bf16 v[18:21], v[212:215], v[168:171], v[18:21]
	v_mfma_f32_16x16x32_bf16 v[14:17], v[212:215], v[188:191], v[14:17]
	v_mfma_f32_16x16x32_bf16 v[2:5], v[216:219], v[168:171], v[2:5]
	v_mfma_f32_16x16x32_bf16 v[90:93], v[216:219], v[188:191], v[90:93]
	s_cbranch_scc0 .LBB0_2714
	s_waitcnt vmcnt(0)
	s_barrier
	v_add_u32_e32 v130, v153, v141
	ds_read_b128 v[132:135], v130
	ds_read_b128 v[164:167], v130 offset:2048
	ds_read_b128 v[168:171], v130 offset:4096
	ds_read_b128 v[172:175], v130 offset:6144
	v_add_u32_e32 v130, v154, v141
	ds_read_b128 v[176:179], v130
	ds_read_b128 v[180:183], v130 offset:2048
	ds_read_b128 v[184:187], v130 offset:4096
	ds_read_b128 v[188:191], v130 offset:6144
	s_waitcnt lgkmcnt(0)
	v_mfma_f32_16x16x32_bf16 v[126:129], v[132:135], v[176:179], v[126:129]
	v_mfma_f32_16x16x32_bf16 v[110:113], v[164:167], v[176:179], v[110:113]
	v_mfma_f32_16x16x32_bf16 v[82:85], v[168:171], v[176:179], v[82:85]
	v_mfma_f32_16x16x32_bf16 v[50:53], v[172:175], v[176:179], v[50:53]
	ds_read_b128 v[176:179], v130 offset:8192
	ds_read_b128 v[192:195], v130 offset:10240
	v_mfma_f32_16x16x32_bf16 v[122:125], v[132:135], v[180:183], v[122:125]
	v_mfma_f32_16x16x32_bf16 v[106:109], v[164:167], v[180:183], v[106:109]
	v_mfma_f32_16x16x32_bf16 v[78:81], v[168:171], v[180:183], v[78:81]
	v_mfma_f32_16x16x32_bf16 v[42:45], v[172:175], v[180:183], v[42:45]
	v_mfma_f32_16x16x32_bf16 v[118:121], v[132:135], v[184:187], v[118:121]
	v_mfma_f32_16x16x32_bf16 v[180:183], v[164:167], v[184:187], v[94:97]
	v_mfma_f32_16x16x32_bf16 v[200:203], v[168:171], v[184:187], v[58:61]
	v_mfma_f32_16x16x32_bf16 v[204:207], v[168:171], v[188:191], v[54:57]
	v_mfma_f32_16x16x32_bf16 v[184:187], v[172:175], v[184:187], v[26:29]
	s_nop 2
	ds_read_b128 v[26:29], v130 offset:12288
	ds_read_b128 v[54:57], v130 offset:14336
	v_mfma_f32_16x16x32_bf16 v[114:117], v[132:135], v[188:191], v[114:117]
	v_mfma_f32_16x16x32_bf16 v[196:199], v[164:167], v[188:191], v[86:89]
	v_mfma_f32_16x16x32_bf16 v[188:191], v[172:175], v[188:191], v[22:25]
	v_add_u32_e32 v130, v154, v142
	s_waitcnt lgkmcnt(0)
	v_mfma_f32_16x16x32_bf16 v[208:211], v[168:171], v[192:195], v[30:33]
	ds_read_b128 v[22:25], v130
	ds_read_b128 v[86:89], v130 offset:2048
	s_nop 0
	v_add_u32_e32 v30, v153, v142
	v_mfma_f32_16x16x32_bf16 v[102:105], v[132:135], v[176:179], v[102:105]
	v_mfma_f32_16x16x32_bf16 v[74:77], v[164:167], v[176:179], v[74:77]
	v_mfma_f32_16x16x32_bf16 v[46:49], v[168:171], v[176:179], v[46:49]
	v_mfma_f32_16x16x32_bf16 v[10:13], v[172:175], v[176:179], v[10:13]
	ds_read_b128 v[176:179], v30
	ds_read_b128 v[212:215], v30 offset:2048
	ds_read_b128 v[216:219], v30 offset:4096
	ds_read_b128 v[220:223], v30 offset:6144
	v_mfma_f32_16x16x32_bf16 v[98:101], v[132:135], v[192:195], v[98:101]
	v_mfma_f32_16x16x32_bf16 v[66:69], v[164:167], v[192:195], v[66:69]
	v_mfma_f32_16x16x32_bf16 v[6:9], v[172:175], v[192:195], v[6:9]
	v_mfma_f32_16x16x32_bf16 v[192:195], v[164:167], v[26:29], v[38:41]
	v_mfma_f32_16x16x32_bf16 v[34:37], v[164:167], v[54:57], v[34:37]
	v_mfma_f32_16x16x32_bf16 v[164:167], v[168:171], v[26:29], v[18:21]
	v_mfma_f32_16x16x32_bf16 v[168:171], v[168:171], v[54:57], v[14:17]
	s_nop 2
	ds_read_b128 v[14:17], v130 offset:4096
	ds_read_b128 v[18:21], v130 offset:6144
	v_mfma_f32_16x16x32_bf16 v[70:73], v[132:135], v[26:29], v[70:73]
	v_mfma_f32_16x16x32_bf16 v[132:135], v[132:135], v[54:57], v[62:65]
	v_mfma_f32_16x16x32_bf16 v[2:5], v[172:175], v[26:29], v[2:5]
	v_mfma_f32_16x16x32_bf16 v[172:175], v[172:175], v[54:57], v[90:93]
	ds_read_b128 v[224:227], v130 offset:8192
	ds_read_b128 v[228:231], v130 offset:10240
	s_waitcnt lgkmcnt(0)
	v_mfma_f32_16x16x32_bf16 v[126:129], v[176:179], v[22:25], v[126:129]
	v_mfma_f32_16x16x32_bf16 v[122:125], v[176:179], v[86:89], v[122:125]
	v_mfma_f32_16x16x32_bf16 v[94:97], v[212:215], v[22:25], v[110:113]
	v_mfma_f32_16x16x32_bf16 v[90:93], v[212:215], v[86:89], v[106:109]
	v_mfma_f32_16x16x32_bf16 v[62:65], v[216:219], v[22:25], v[82:85]
	v_mfma_f32_16x16x32_bf16 v[58:61], v[216:219], v[86:89], v[78:81]
	v_mfma_f32_16x16x32_bf16 v[30:33], v[220:223], v[22:25], v[50:53]
	v_mfma_f32_16x16x32_bf16 v[26:29], v[220:223], v[86:89], v[42:45]
	v_mfma_f32_16x16x32_bf16 v[86:89], v[212:215], v[14:17], v[180:183]
	v_mfma_f32_16x16x32_bf16 v[22:25], v[220:223], v[14:17], v[184:187]
	s_nop 1
	ds_read_b128 v[180:183], v130 offset:12288
	ds_read_b128 v[184:187], v130 offset:14336
	v_mfma_f32_16x16x32_bf16 v[118:121], v[176:179], v[14:17], v[118:121]
	v_mfma_f32_16x16x32_bf16 v[114:117], v[176:179], v[18:21], v[114:117]
	v_mfma_f32_16x16x32_bf16 v[82:85], v[212:215], v[18:21], v[196:199]
	v_mfma_f32_16x16x32_bf16 v[54:57], v[216:219], v[14:17], v[200:203]
	v_mfma_f32_16x16x32_bf16 v[50:53], v[216:219], v[18:21], v[204:207]
	v_mfma_f32_16x16x32_bf16 v[18:21], v[220:223], v[18:21], v[188:191]
	v_mfma_f32_16x16x32_bf16 v[110:113], v[176:179], v[224:227], v[102:105]
	v_mfma_f32_16x16x32_bf16 v[106:109], v[176:179], v[228:231], v[98:101]
	v_mfma_f32_16x16x32_bf16 v[78:81], v[212:215], v[224:227], v[74:77]
	v_mfma_f32_16x16x32_bf16 v[74:77], v[212:215], v[228:231], v[66:69]
	v_mfma_f32_16x16x32_bf16 v[46:49], v[216:219], v[224:227], v[46:49]
	v_mfma_f32_16x16x32_bf16 v[38:41], v[216:219], v[228:231], v[208:211]
	v_mfma_f32_16x16x32_bf16 v[14:17], v[220:223], v[224:227], v[10:13]
	v_mfma_f32_16x16x32_bf16 v[6:9], v[220:223], v[228:231], v[6:9]
	v_mov_b32_e32 v130, v1
	s_waitcnt vmcnt(0) lgkmcnt(0)
	s_barrier
; __device__ __forceinline__ int get_tid512() { int t = threadIdx.x; asm volatile("" : "+v"(t)); return t; }
; __device__ __forceinline__ unsigned pack2(float a, float b) { unsigned r; asm("v_cvt_pk_bf16_f32 %0, %1, %2" : "=v"(r) : "v"(a), "v"(b)); return r; }
;   __device__ __forceinline__ void r4(int g, int rig, int col, f32x4 v) const {
;     const float b = bias[col];
;     uint2 u; u.x = pack2(v[0] + b, v[1] + b); u.y = pack2(v[2] + b, v[3] + b);
;     *(uint2*)(out + (size_t)col * 16384 + (size_t)g * 2048 + rig) = u;
;   }
; template <bool SWAP, class Epi, bool THIN = false> ...
;     ...
;     const int te = get_tid512();
;     const int fr_e = te & 15, fq_e = (te & 63) >> 4, wr_e = te >> 7, wc_e = (te >> 6) & 1;
;     const int sub = 2 * mt + (wr_e >> 1);
;     const int g = sub / tpg, ti = sub - g * tpg;
;     const int rig0 = ti * step - halo;
;     const int rw = (wr_e & 1) * 64;
;     if constexpr (Epi::KIND == 0) {
; #pragma unroll
;       for (int m = 0; m < 4; ++m) {
;         const int rig = rig0 + rw + m * 16 + fr_e;
;         if constexpr (Epi::ROWSUM) {
;           float ss = 0.f;
; #pragma unroll
;           for (int n = 0; n < 8; ++n) {
;             const int col = nt * 256 + wc_e * 128 + n * 16 + fq_e * 4;
;             if (col < N) ss += epi.c4(g, rig, col, acc[m][n]);
;           }
;           ss += __shfl_xor(ss, 16); ss += __shfl_xor(ss, 32);
;           if (fq_e == 0) epi.rowsum(g, rig, nt * 2 + wc_e, ss);
;         } else {
; #pragma unroll
;           for (int n = 0; n < 8; ++n) {
;             const int col = nt * 256 + wc_e * 128 + n * 16 + fq_e * 4;
;             if (col < N) epi.c4(g, rig, col, acc[m][n]);
;           }
;         }
;       }
;     } else if constexpr (Epi::KIND == 1) {
; #pragma unroll
;       for (int m = 0; m < 4; ++m) {
;         const int rig = rig0 + rw + m * 16 + fq_e * 4;
; #pragma unroll
;         for (int n = 0; n < 8; ++n) {
;           const int col = nt * 256 + wc_e * 128 + n * 16 + fr_e;
;           if (col < N) epi.r4(g, rig, col, acc[m][n]);
;         }
;       }
	v_mfma_f32_16x16x32_bf16 v[98:101], v[176:179], v[184:187], v[132:135]
	v_ashrrev_i32_e32 v10, 8, v130
	v_add_u32_e32 v10, s5, v10
	v_ashrrev_i32_e32 v11, 31, v10
	v_lshrrev_b32_e32 v11, 28, v11
	v_add_u32_e32 v11, v10, v11
	v_ashrrev_i32_e32 v132, 4, v11
	v_lshlrev_b32_e32 v11, 11, v132
	v_lshlrev_b32_e32 v10, 7, v10
	v_sub_u32_e32 v10, v10, v11
	v_lshrrev_b32_e32 v11, 1, v130
	v_lshrrev_b32_e32 v12, 2, v130
	v_and_b32_e32 v11, 64, v11
	v_and_b32_e32 v12, 12, v12
	v_mfma_f32_16x16x32_bf16 v[42:45], v[216:219], v[180:183], v[164:167]
	v_and_b32_e32 v133, 15, v130
	s_nop 1
	v_or3_b32 v164, v10, v11, v12
	v_mfma_f32_16x16x32_bf16 v[10:13], v[220:223], v[180:183], v[2:5]
	v_ashrrev_i32_e32 v165, 31, v164
	s_nop 1
	v_lshlrev_b32_e32 v2, 1, v130
	v_and_b32_e32 v2, 0x80, v2
	v_mfma_f32_16x16x32_bf16 v[102:105], v[176:179], v[180:183], v[70:73]
	v_or3_b32 v134, v133, v2, s4
	v_ashrrev_i32_e32 v133, 31, v132
	v_lshlrev_b64 v[132:133], 12, v[132:133]
	v_mfma_f32_16x16x32_bf16 v[70:73], v[212:215], v[180:183], v[192:195]
	v_lshl_add_u64 v[132:133], s[20:21], 0, v[132:133]
	v_lshl_add_u64 v[132:133], v[164:165], 1, v[132:133]
	v_cmp_gt_i32_e32 vcc, s30, v134
	v_mfma_f32_16x16x32_bf16 v[66:69], v[212:215], v[184:187], v[34:37]
	v_ashrrev_i32_e32 v135, 31, v134
	v_mfma_f32_16x16x32_bf16 v[34:37], v[216:219], v[184:187], v[168:171]
	v_mfma_f32_16x16x32_bf16 v[2:5], v[220:223], v[184:187], v[172:175]
	v_lshlrev_b32_e32 v236, 2, v134
	global_load_dword v237, v236, s[22:23]
	global_load_dword v238, v236, s[22:23] offset:64
	global_load_dword v239, v236, s[22:23] offset:128
	global_load_dword v240, v236, s[22:23] offset:192
	global_load_dword v241, v236, s[22:23] offset:256
	global_load_dword v242, v236, s[22:23] offset:320
	global_load_dword v243, v236, s[22:23] offset:384
	global_load_dword v244, v236, s[22:23] offset:448
	s_waitcnt vmcnt(0)
	v_bfe_u32 v246, v1, 4, 1
	v_mul_u32_u24_e32 v246, 24, v246
	v_mov_b32_e32 v247, 0
	v_lshlrev_b64 v[232:233], 15, v[134:135]
	v_lshl_add_u64 v[234:235], v[132:133], 0, v[232:233]
	v_lshl_add_u64 v[234:235], v[234:235], 0, v[246:247]
	v_add_f32_e32 v126, v126, v237
	v_add_f32_e32 v127, v127, v237
	v_add_f32_e32 v128, v128, v237
	v_add_f32_e32 v129, v129, v237
	v_add_f32_e32 v94, v94, v237
	v_add_f32_e32 v95, v95, v237
	v_add_f32_e32 v96, v96, v237
	v_add_f32_e32 v97, v97, v237
	v_cvt_pk_bf16_f32 v126, v126, v127
	v_cvt_pk_bf16_f32 v127, v128, v129
	v_cvt_pk_bf16_f32 v128, v94, v95
	v_cvt_pk_bf16_f32 v129, v96, v97
	s_nop 1
	v_permlane16_swap_b32 v126, v128
	v_permlane16_swap_b32 v127, v129
	global_store_dwordx4 v[234:235], v[126:129], off
	v_add_f32_e32 v62, v62, v237
	v_add_f32_e32 v63, v63, v237
	v_add_f32_e32 v64, v64, v237
	v_add_f32_e32 v65, v65, v237
	v_add_f32_e32 v30, v30, v237
	v_add_f32_e32 v31, v31, v237
	v_add_f32_e32 v32, v32, v237
	v_add_f32_e32 v33, v33, v237
	v_cvt_pk_bf16_f32 v62, v62, v63
	v_cvt_pk_bf16_f32 v63, v64, v65
	v_cvt_pk_bf16_f32 v64, v30, v31
	v_cvt_pk_bf16_f32 v65, v32, v33
	s_nop 1
	v_permlane16_swap_b32 v62, v64
	v_permlane16_swap_b32 v63, v65
	global_store_dwordx4 v[234:235], v[62:65], off offset:64
	s_nop 1
	v_or_b32_e32 v232, 16, v134
	v_ashrrev_i32_e32 v233, 31, v232
	v_lshlrev_b64 v[232:233], 15, v[232:233]
	v_lshl_add_u64 v[234:235], v[132:133], 0, v[232:233]
	v_lshl_add_u64 v[234:235], v[234:235], 0, v[246:247]
	v_add_f32_e32 v122, v122, v238
	v_add_f32_e32 v123, v123, v238
	v_add_f32_e32 v124, v124, v238
	v_add_f32_e32 v125, v125, v238
	v_add_f32_e32 v90, v90, v238
	v_add_f32_e32 v91, v91, v238
	v_add_f32_e32 v92, v92, v238
	v_add_f32_e32 v93, v93, v238
	v_cvt_pk_bf16_f32 v122, v122, v123
	v_cvt_pk_bf16_f32 v123, v124, v125
	v_cvt_pk_bf16_f32 v124, v90, v91
	v_cvt_pk_bf16_f32 v125, v92, v93
	s_nop 1
	v_permlane16_swap_b32 v122, v124
	v_permlane16_swap_b32 v123, v125
	global_store_dwordx4 v[234:235], v[122:125], off
	v_add_f32_e32 v58, v58, v238
	v_add_f32_e32 v59, v59, v238
	v_add_f32_e32 v60, v60, v238
	v_add_f32_e32 v61, v61, v238
	v_add_f32_e32 v26, v26, v238
	v_add_f32_e32 v27, v27, v238
	v_add_f32_e32 v28, v28, v238
	v_add_f32_e32 v29, v29, v238
	v_cvt_pk_bf16_f32 v58, v58, v59
	v_cvt_pk_bf16_f32 v59, v60, v61
	v_cvt_pk_bf16_f32 v60, v26, v27
	v_cvt_pk_bf16_f32 v61, v28, v29
	s_nop 1
	v_permlane16_swap_b32 v58, v60
	v_permlane16_swap_b32 v59, v61
	global_store_dwordx4 v[234:235], v[58:61], off offset:64
	s_nop 1
	v_or_b32_e32 v232, 32, v134
	v_ashrrev_i32_e32 v233, 31, v232
	v_lshlrev_b64 v[232:233], 15, v[232:233]
	v_lshl_add_u64 v[234:235], v[132:133], 0, v[232:233]
	v_lshl_add_u64 v[234:235], v[234:235], 0, v[246:247]
	v_add_f32_e32 v118, v118, v239
	v_add_f32_e32 v119, v119, v239
	v_add_f32_e32 v120, v120, v239
	v_add_f32_e32 v121, v121, v239
	v_add_f32_e32 v86, v86, v239
	v_add_f32_e32 v87, v87, v239
	v_add_f32_e32 v88, v88, v239
	v_add_f32_e32 v89, v89, v239
	v_cvt_pk_bf16_f32 v118, v118, v119
	v_cvt_pk_bf16_f32 v119, v120, v121
	v_cvt_pk_bf16_f32 v120, v86, v87
	v_cvt_pk_bf16_f32 v121, v88, v89
	s_nop 1
	v_permlane16_swap_b32 v118, v120
	v_permlane16_swap_b32 v119, v121
	global_store_dwordx4 v[234:235], v[118:121], off
	v_add_f32_e32 v54, v54, v239
	v_add_f32_e32 v55, v55, v239
	v_add_f32_e32 v56, v56, v239
	v_add_f32_e32 v57, v57, v239
	v_add_f32_e32 v22, v22, v239
	v_add_f32_e32 v23, v23, v239
	v_add_f32_e32 v24, v24, v239
	v_add_f32_e32 v25, v25, v239
	v_cvt_pk_bf16_f32 v54, v54, v55
	v_cvt_pk_bf16_f32 v55, v56, v57
	v_cvt_pk_bf16_f32 v56, v22, v23
	v_cvt_pk_bf16_f32 v57, v24, v25
	s_nop 1
	v_permlane16_swap_b32 v54, v56
	v_permlane16_swap_b32 v55, v57
	global_store_dwordx4 v[234:235], v[54:57], off offset:64
	s_nop 1
	v_or_b32_e32 v232, 48, v134
; __device__ __forceinline__ unsigned pack2(float a, float b) { unsigned r; asm("v_cvt_pk_bf16_f32 %0, %1, %2" : "=v"(r) : "v"(a), "v"(b)); return r; }
;   __device__ __forceinline__ void r4(int g, int rig, int col, f32x4 v) const {
;     const float b = bias[col];
;     uint2 u; u.x = pack2(v[0] + b, v[1] + b); u.y = pack2(v[2] + b, v[3] + b);
;     *(uint2*)(out + (size_t)col * 16384 + (size_t)g * 2048 + rig) = u;
;   }
; template <bool SWAP, class Epi, bool THIN = false> ...
;     ...
;     } else if constexpr (Epi::KIND == 1) {
; #pragma unroll
;       for (int m = 0; m < 4; ++m) {
;         const int rig = rig0 + rw + m * 16 + fq_e * 4;
; #pragma unroll
;         for (int n = 0; n < 8; ++n) {
;           const int col = nt * 256 + wc_e * 128 + n * 16 + fr_e;
;           if (col < N) epi.r4(g, rig, col, acc[m][n]);
;         }
;       }
	v_ashrrev_i32_e32 v233, 31, v232
	v_lshlrev_b64 v[232:233], 15, v[232:233]
	v_lshl_add_u64 v[234:235], v[132:133], 0, v[232:233]
	v_lshl_add_u64 v[234:235], v[234:235], 0, v[246:247]
	v_add_f32_e32 v114, v114, v240
	v_add_f32_e32 v115, v115, v240
	v_add_f32_e32 v116, v116, v240
	v_add_f32_e32 v117, v117, v240
	v_add_f32_e32 v82, v82, v240
	v_add_f32_e32 v83, v83, v240
	v_add_f32_e32 v84, v84, v240
	v_add_f32_e32 v85, v85, v240
	v_cvt_pk_bf16_f32 v114, v114, v115
	v_cvt_pk_bf16_f32 v115, v116, v117
	v_cvt_pk_bf16_f32 v116, v82, v83
	v_cvt_pk_bf16_f32 v117, v84, v85
	s_nop 1
	v_permlane16_swap_b32 v114, v116
	v_permlane16_swap_b32 v115, v117
	global_store_dwordx4 v[234:235], v[114:117], off
	v_add_f32_e32 v50, v50, v240
	v_add_f32_e32 v51, v51, v240
	v_add_f32_e32 v52, v52, v240
	v_add_f32_e32 v53, v53, v240
	v_add_f32_e32 v18, v18, v240
	v_add_f32_e32 v19, v19, v240
	v_add_f32_e32 v20, v20, v240
	v_add_f32_e32 v21, v21, v240
	v_cvt_pk_bf16_f32 v50, v50, v51
	v_cvt_pk_bf16_f32 v51, v52, v53
	v_cvt_pk_bf16_f32 v52, v18, v19
	v_cvt_pk_bf16_f32 v53, v20, v21
	s_nop 1
	v_permlane16_swap_b32 v50, v52
	v_permlane16_swap_b32 v51, v53
	global_store_dwordx4 v[234:235], v[50:53], off offset:64
	s_nop 1
	v_or_b32_e32 v232, 64, v134
	v_ashrrev_i32_e32 v233, 31, v232
	v_lshlrev_b64 v[232:233], 15, v[232:233]
	v_lshl_add_u64 v[234:235], v[132:133], 0, v[232:233]
	v_lshl_add_u64 v[234:235], v[234:235], 0, v[246:247]
	v_add_f32_e32 v110, v110, v241
	v_add_f32_e32 v111, v111, v241
	v_add_f32_e32 v112, v112, v241
	v_add_f32_e32 v113, v113, v241
	v_add_f32_e32 v78, v78, v241
	v_add_f32_e32 v79, v79, v241
	v_add_f32_e32 v80, v80, v241
	v_add_f32_e32 v81, v81, v241
	v_cvt_pk_bf16_f32 v110, v110, v111
	v_cvt_pk_bf16_f32 v111, v112, v113
	v_cvt_pk_bf16_f32 v112, v78, v79
	v_cvt_pk_bf16_f32 v113, v80, v81
	s_nop 1
	v_permlane16_swap_b32 v110, v112
	v_permlane16_swap_b32 v111, v113
	global_store_dwordx4 v[234:235], v[110:113], off
	v_add_f32_e32 v46, v46, v241
	v_add_f32_e32 v47, v47, v241
	v_add_f32_e32 v48, v48, v241
	v_add_f32_e32 v49, v49, v241
	v_add_f32_e32 v14, v14, v241
	v_add_f32_e32 v15, v15, v241
	v_add_f32_e32 v16, v16, v241
	v_add_f32_e32 v17, v17, v241
	v_cvt_pk_bf16_f32 v46, v46, v47
	v_cvt_pk_bf16_f32 v47, v48, v49
	v_cvt_pk_bf16_f32 v48, v14, v15
	v_cvt_pk_bf16_f32 v49, v16, v17
	s_nop 1
	v_permlane16_swap_b32 v46, v48
	v_permlane16_swap_b32 v47, v49
	global_store_dwordx4 v[234:235], v[46:49], off offset:64
	s_nop 1
	v_or_b32_e32 v232, 80, v134
	v_ashrrev_i32_e32 v233, 31, v232
	v_lshlrev_b64 v[232:233], 15, v[232:233]
	v_lshl_add_u64 v[234:235], v[132:133], 0, v[232:233]
	v_lshl_add_u64 v[234:235], v[234:235], 0, v[246:247]
	v_add_f32_e32 v106, v106, v242
	v_add_f32_e32 v107, v107, v242
	v_add_f32_e32 v108, v108, v242
	v_add_f32_e32 v109, v109, v242
	v_add_f32_e32 v74, v74, v242
	v_add_f32_e32 v75, v75, v242
	v_add_f32_e32 v76, v76, v242
	v_add_f32_e32 v77, v77, v242
	v_cvt_pk_bf16_f32 v106, v106, v107
	v_cvt_pk_bf16_f32 v107, v108, v109
	v_cvt_pk_bf16_f32 v108, v74, v75
	v_cvt_pk_bf16_f32 v109, v76, v77
	s_nop 1
	v_permlane16_swap_b32 v106, v108
	v_permlane16_swap_b32 v107, v109
	global_store_dwordx4 v[234:235], v[106:109], off
	v_add_f32_e32 v38, v38, v242
	v_add_f32_e32 v39, v39, v242
	v_add_f32_e32 v40, v40, v242
	v_add_f32_e32 v41, v41, v242
	v_add_f32_e32 v6, v6, v242
	v_add_f32_e32 v7, v7, v242
	v_add_f32_e32 v8, v8, v242
	v_add_f32_e32 v9, v9, v242
	v_cvt_pk_bf16_f32 v38, v38, v39
	v_cvt_pk_bf16_f32 v39, v40, v41
	v_cvt_pk_bf16_f32 v40, v6, v7
	v_cvt_pk_bf16_f32 v41, v8, v9
	s_nop 1
	v_permlane16_swap_b32 v38, v40
	v_permlane16_swap_b32 v39, v41
	global_store_dwordx4 v[234:235], v[38:41], off offset:64
	s_nop 1
	v_or_b32_e32 v232, 96, v134
	v_ashrrev_i32_e32 v233, 31, v232
	v_lshlrev_b64 v[232:233], 15, v[232:233]
	v_lshl_add_u64 v[234:235], v[132:133], 0, v[232:233]
	v_lshl_add_u64 v[234:235], v[234:235], 0, v[246:247]
	v_add_f32_e32 v102, v102, v243
	v_add_f32_e32 v103, v103, v243
	v_add_f32_e32 v104, v104, v243
	v_add_f32_e32 v105, v105, v243
	v_add_f32_e32 v70, v70, v243
	v_add_f32_e32 v71, v71, v243
	v_add_f32_e32 v72, v72, v243
	v_add_f32_e32 v73, v73, v243
	v_cvt_pk_bf16_f32 v102, v102, v103
	v_cvt_pk_bf16_f32 v103, v104, v105
	v_cvt_pk_bf16_f32 v104, v70, v71
	v_cvt_pk_bf16_f32 v105, v72, v73
	s_nop 1
	v_permlane16_swap_b32 v102, v104
	v_permlane16_swap_b32 v103, v105
	global_store_dwordx4 v[234:235], v[102:105], off
	v_add_f32_e32 v42, v42, v243
	v_add_f32_e32 v43, v43, v243
	v_add_f32_e32 v44, v44, v243
	v_add_f32_e32 v45, v45, v243
	v_add_f32_e32 v10, v10, v243
	v_add_f32_e32 v11, v11, v243
	v_add_f32_e32 v12, v12, v243
	v_add_f32_e32 v13, v13, v243
	v_cvt_pk_bf16_f32 v42, v42, v43
	v_cvt_pk_bf16_f32 v43, v44, v45
	v_cvt_pk_bf16_f32 v44, v10, v11
	v_cvt_pk_bf16_f32 v45, v12, v13
	s_nop 1
	v_permlane16_swap_b32 v42, v44
	v_permlane16_swap_b32 v43, v45
	global_store_dwordx4 v[234:235], v[42:45], off offset:64
	s_nop 1
	v_or_b32_e32 v232, 112, v134
	v_ashrrev_i32_e32 v233, 31, v232
	v_lshlrev_b64 v[232:233], 15, v[232:233]
	v_lshl_add_u64 v[234:235], v[132:133], 0, v[232:233]
	v_lshl_add_u64 v[234:235], v[234:235], 0, v[246:247]
	v_add_f32_e32 v98, v98, v244
	v_add_f32_e32 v99, v99, v244
	v_add_f32_e32 v100, v100, v244
	v_add_f32_e32 v101, v101, v244
	v_add_f32_e32 v66, v66, v244
	v_add_f32_e32 v67, v67, v244
	v_add_f32_e32 v68, v68, v244
	v_add_f32_e32 v69, v69, v244
	v_cvt_pk_bf16_f32 v98, v98, v99
	v_cvt_pk_bf16_f32 v99, v100, v101
	v_cvt_pk_bf16_f32 v100, v66, v67
	v_cvt_pk_bf16_f32 v101, v68, v69
	s_nop 1
	v_permlane16_swap_b32 v98, v100
	v_permlane16_swap_b32 v99, v101
	global_store_dwordx4 v[234:235], v[98:101], off
	v_add_f32_e32 v34, v34, v244
	v_add_f32_e32 v35, v35, v244
	v_add_f32_e32 v36, v36, v244
	v_add_f32_e32 v37, v37, v244
	v_add_f32_e32 v2, v2, v244
	v_add_f32_e32 v3, v3, v244
	v_add_f32_e32 v4, v4, v244
	v_add_f32_e32 v5, v5, v244
	v_cvt_pk_bf16_f32 v34, v34, v35
	v_cvt_pk_bf16_f32 v35, v36, v37
	v_cvt_pk_bf16_f32 v36, v2, v3
	v_cvt_pk_bf16_f32 v37, v4, v5
	s_nop 1
	v_permlane16_swap_b32 v34, v36
	v_permlane16_swap_b32 v35, v37
	global_store_dwordx4 v[234:235], v[34:37], off offset:64
	s_nop 1
	s_branch .LBB0_2712
